# vAA + attention row-max 16-lane step via v_permlane16_swap_b32 instead of ds_swizzle SWAP,16 (18 sites in the dilated/stick-breaking loops; removes an LDS round trip from the serial softmax chain)
# speedup vs baseline: 1.0036x; 1.0036x over previous
.LBB0_367:
	s_add_i32 s62, s63, 3
	s_add_i32 s38, s61, -16
	s_cmp_lt_i32 s62, 8
	s_cselect_b64 s[0:1], -1, 0
	s_and_b64 s[4:5], s[0:1], exec
	s_cselect_b32 s4, s38, 0x90
	s_add_i32 s4, s4, s57
	s_waitcnt vmcnt(11)
	v_or_b32_e32 v64, s4, v149
	v_med3_i32 v64, v64, 0, v244
	v_add_u32_e32 v65, s4, v194
	v_med3_i32 v65, v65, 0, v244
	v_mul_u32_u24_e32 v176, 0x2800, v64
	s_waitcnt vmcnt(10)
	v_lshl_add_u64 v[68:69], v[164:165], 0, v[176:177]
	v_mul_u32_u24_e32 v176, 0x2800, v65
	s_waitcnt vmcnt(8) lgkmcnt(1)
	v_lshl_add_u64 v[92:93], v[166:167], 0, v[176:177]
	global_load_dwordx4 v[64:67], v[68:69], off offset:1536
	s_nop 0
	global_load_dwordx4 v[68:71], v[68:69], off offset:1600
	s_nop 0
	global_load_dwordx4 v[88:91], v[92:93], off offset:3088
	s_waitcnt lgkmcnt(0)
	global_load_dwordx4 v[92:95], v[92:93], off offset:3072
	s_waitcnt vmcnt(6)
	ds_write_b128 v211, v[76:79]
	ds_write_b128 v211, v[72:75] offset:16
	ds_read_b64_tr_b16 v[72:73], v212
	ds_read_b64_tr_b16 v[74:75], v212 offset:32
	ds_read_b64_tr_b16 v[76:77], v212 offset:64
	ds_read_b64_tr_b16 v[78:79], v212 offset:96
	v_add_u32_e32 v104, s61, v102
	v_add_u32_e32 v105, 0xffffff50, v104
	s_cmp_lg_u32 s63, 6
	s_cselect_b64 s[4:5], -1, 0
	s_cmp_eq_u32 s63, 6
	v_add_u32_e32 v103, s61, v200
	v_cmp_lt_i32_e64 s[48:49], -1, v105
	v_cmp_lt_i32_e64 s[46:47], -2, v105
	v_cmp_lt_i32_e64 s[44:45], -3, v105
	v_cmp_lt_i32_e32 vcc, -4, v105
	s_cbranch_scc1 .LBB0_372
	v_subrev_u32_e32 v101, 48, v103
	v_cmp_gt_u32_e64 s[50:51], s16, v101
	s_waitcnt vmcnt(4)
	s_nop 1
	v_mfma_f32_16x16x32_bf16 v[106:109], v[52:55], v[12:15], 0
	v_mfma_f32_16x16x32_bf16 v[106:109], v[48:51], v[20:23], v[106:109]
	s_nop 7
	v_add_u32_e32 v100, 0xffffff50, v103
	s_and_b64 s[48:49], s[48:49], s[50:51]
	v_cndmask_b32_e64 v106, v245, v106, s[48:49]
	v_cmp_lt_u32_e64 s[48:49], s17, v100
	s_and_b64 s[46:47], s[46:47], s[48:49]
	v_subrev_u32_e32 v100, 46, v103
	v_cndmask_b32_e64 v107, v245, v107, s[46:47]
	v_cmp_gt_u32_e64 s[46:47], s16, v100
	s_and_b64 s[44:45], s[44:45], s[46:47]
	v_subrev_u32_e32 v100, 45, v103
	v_cndmask_b32_e64 v108, v245, v108, s[44:45]
	v_cmp_gt_u32_e64 s[44:45], s16, v100
	s_and_b64 vcc, vcc, s[44:45]
	v_cndmask_b32_e32 v109, v245, v109, vcc
	v_max_f32_e32 v100, v109, v109
	v_max_f32_e32 v101, v108, v108
	v_max_f32_e32 v100, v101, v100
	v_max3_f32 v100, v106, v107, v100
	v_mov_b32_e32 v101, v100
	s_nop 1
	v_permlane16_swap_b32_e32 v100, v101
	s_waitcnt lgkmcnt(0)
	v_max_f32_e32 v101, v101, v101
	v_max_f32_e32 v100, v100, v101
	v_mov_b32_e32 v101, v100
	s_nop 1
	v_permlane32_swap_b32_e32 v100, v101
	v_max_f32_e32 v101, v101, v101
	v_max_f32_e32 v100, v100, v100
	v_max_f32_e32 v100, v100, v101
	v_mul_f32_e32 v100, 0x3e38aa3b, v100
	v_add_f32_e32 v101, 0x41000000, v98
	v_cmp_gt_f32_e32 vcc, v100, v101
	s_cbranch_vccz .LBB0_370
	s_nop 0
	v_cndmask_b32_e32 v100, v98, v100, vcc
	v_sub_f32_e32 v98, v98, v100
	v_exp_f32_e32 v98, v98
	v_mov_b32_e32 v101, v99
	v_mul_f32_e32 v96, v96, v98
	v_pk_mul_f32 v[46:47], v[46:47], v[98:99] op_sel_hi:[1,0]
	v_pk_mul_f32 v[44:45], v[44:45], v[98:99] op_sel_hi:[1,0]
	v_pk_mul_f32 v[38:39], v[38:39], v[98:99] op_sel_hi:[1,0]
	v_pk_mul_f32 v[36:37], v[36:37], v[98:99] op_sel_hi:[1,0]
	v_pk_mul_f32 v[42:43], v[42:43], v[98:99] op_sel_hi:[1,0]
	v_pk_mul_f32 v[40:41], v[40:41], v[98:99] op_sel_hi:[1,0]
	v_pk_mul_f32 v[34:35], v[34:35], v[98:99] op_sel_hi:[1,0]
	v_pk_mul_f32 v[32:33], v[32:33], v[98:99] op_sel_hi:[1,0]
	v_mov_b64_e32 v[98:99], v[100:101]
	s_branch .LBB0_371

.LBB0_372:
	s_cmp_lt_i32 s62, 1
	s_cbranch_scc1 .LBB0_377
	s_waitcnt vmcnt(4)
	s_nop 1
	v_mfma_f32_16x16x32_bf16 v[106:109], v[52:55], v[24:27], 0
	v_mfma_f32_16x16x32_bf16 v[106:109], v[48:51], v[28:31], v[106:109]
	s_nop 7
	v_subrev_u32_e32 v48, 64, v103
	v_cmp_gt_u32_e32 vcc, s16, v48
	v_cmp_lt_i32_e64 s[44:45], -1, v105
	v_add_u32_e32 v49, 0xffffff40, v103
	s_and_b64 vcc, s[44:45], vcc
	v_cndmask_b32_e32 v48, v245, v106, vcc
	v_cmp_lt_u32_e32 vcc, s17, v49
	v_cmp_lt_i32_e64 s[44:45], -2, v105
	s_and_b64 vcc, s[44:45], vcc
	v_subrev_u32_e32 v50, 62, v103
	v_cndmask_b32_e32 v49, v245, v107, vcc
	v_cmp_gt_u32_e32 vcc, s16, v50
	v_cmp_lt_i32_e64 s[44:45], -3, v105
	s_and_b64 vcc, s[44:45], vcc
	v_subrev_u32_e32 v51, 61, v103
	v_cndmask_b32_e32 v50, v245, v108, vcc
	v_cmp_gt_u32_e32 vcc, s16, v51
	v_cmp_lt_i32_e64 s[44:45], -4, v105
	s_and_b64 vcc, s[44:45], vcc
	v_cndmask_b32_e32 v51, v245, v109, vcc
	v_max_f32_e32 v52, v51, v51
	v_max_f32_e32 v53, v50, v50
	v_max_f32_e32 v52, v53, v52
	v_max3_f32 v52, v48, v49, v52
	v_mov_b32_e32 v53, v52
	s_nop 1
	v_permlane16_swap_b32_e32 v52, v53
	s_waitcnt lgkmcnt(0)
	v_max_f32_e32 v53, v53, v53
	v_max_f32_e32 v52, v52, v53
	v_mov_b32_e32 v53, v52
	s_nop 1
	v_permlane32_swap_b32_e32 v52, v53
	v_max_f32_e32 v53, v53, v53
	v_max_f32_e32 v52, v52, v52
	v_max_f32_e32 v52, v52, v53
	v_mul_f32_e32 v52, 0x3e38aa3b, v52
	v_add_f32_e32 v53, 0x41000000, v99
	v_cmp_gt_f32_e32 vcc, v52, v53
	s_cbranch_vccz .LBB0_375
	s_nop 0
	v_cndmask_b32_e32 v52, v99, v52, vcc
	v_sub_f32_e32 v53, v99, v52
	v_exp_f32_e32 v54, v53
	v_mov_b32_e32 v99, v52
	v_mul_f32_e32 v97, v97, v54
	v_pk_mul_f32 v[18:19], v[18:19], v[54:55] op_sel_hi:[1,0]
	v_pk_mul_f32 v[16:17], v[16:17], v[54:55] op_sel_hi:[1,0]
	v_pk_mul_f32 v[10:11], v[10:11], v[54:55] op_sel_hi:[1,0]
	v_pk_mul_f32 v[8:9], v[8:9], v[54:55] op_sel_hi:[1,0]
	v_pk_mul_f32 v[6:7], v[6:7], v[54:55] op_sel_hi:[1,0]
	v_pk_mul_f32 v[4:5], v[4:5], v[54:55] op_sel_hi:[1,0]
	v_pk_mul_f32 v[2:3], v[2:3], v[54:55] op_sel_hi:[1,0]
	v_pk_mul_f32 v[0:1], v[0:1], v[54:55] op_sel_hi:[1,0]
	s_branch .LBB0_376

.LBB0_377:
	s_cmp_gt_i32 s62, 6
	s_cselect_b64 s[38:39], -1, 0
	s_cmp_lt_i32 s62, 7
	s_cselect_b32 s44, s61, 0x90
	s_add_i32 s44, s44, s57
	s_waitcnt vmcnt(5)
	v_or_b32_e32 v48, s44, v149
	v_med3_i32 v48, v48, 0, v244
	v_add_u32_e32 v49, s44, v194
	v_med3_i32 v50, v49, 0, v244
	v_mul_u32_u24_e32 v176, 0x2800, v48
	v_lshl_add_u64 v[48:49], v[164:165], 0, v[176:177]
	v_mul_u32_u24_e32 v176, 0x2800, v50
	s_waitcnt lgkmcnt(1)
	v_lshl_add_u64 v[76:77], v[166:167], 0, v[176:177]
	global_load_dwordx4 v[52:55], v[48:49], off offset:1536
	s_nop 0
	global_load_dwordx4 v[48:51], v[48:49], off offset:1600
	s_nop 0
	global_load_dwordx4 v[72:75], v[76:77], off offset:3088
	s_waitcnt lgkmcnt(0)
	global_load_dwordx4 v[76:79], v[76:77], off offset:3072
	v_cndmask_b32_e64 v100, 0, 1, s[0:1]
	s_andn2_b64 vcc, exec, s[4:5]
	v_cmp_ne_u32_e64 s[44:45], 1, v100
	s_cbranch_vccnz .LBB0_388
	s_waitcnt vmcnt(8)
	ds_write_b128 v211, v[84:87]
	ds_write_b128 v211, v[80:83] offset:16
	ds_read_b64_tr_b16 v[80:81], v212
	ds_read_b64_tr_b16 v[82:83], v212 offset:32
	ds_read_b64_tr_b16 v[84:85], v212 offset:64
	ds_read_b64_tr_b16 v[86:87], v212 offset:96
	v_add_u32_e32 v105, 0xffffff60, v104
	s_and_b64 vcc, exec, s[44:45]
	v_cmp_lt_i32_e64 s[52:53], -1, v105
	v_cmp_lt_i32_e64 s[50:51], -2, v105
	v_cmp_lt_i32_e64 s[48:49], -3, v105
	v_cmp_lt_i32_e64 s[46:47], -4, v105
	s_cbranch_vccnz .LBB0_383
	v_subrev_u32_e32 v101, 32, v103
	v_cmp_gt_u32_e32 vcc, s16, v101
	s_nop 1
	v_mfma_f32_16x16x32_bf16 v[106:109], v[56:59], v[12:15], 0
	v_mfma_f32_16x16x32_bf16 v[106:109], v[60:63], v[20:23], v[106:109]
	s_nop 7
	v_add_u32_e32 v100, 0xffffff60, v103
	s_and_b64 vcc, s[52:53], vcc
	v_cndmask_b32_e32 v106, v245, v106, vcc
	v_cmp_lt_u32_e32 vcc, s17, v100
	s_and_b64 vcc, s[50:51], vcc
	v_subrev_u32_e32 v100, 30, v103
	v_cndmask_b32_e32 v107, v245, v107, vcc
	v_cmp_gt_u32_e32 vcc, s16, v100
	s_and_b64 vcc, s[48:49], vcc
	v_subrev_u32_e32 v100, 29, v103
	v_cndmask_b32_e32 v108, v245, v108, vcc
	v_cmp_gt_u32_e32 vcc, s16, v100
	s_and_b64 vcc, s[46:47], vcc
	v_max_f32_e32 v101, v108, v108
	v_cndmask_b32_e32 v109, v245, v109, vcc
	v_max_f32_e32 v100, v109, v109
	v_max_f32_e32 v100, v101, v100
	v_max3_f32 v100, v106, v107, v100
	v_mov_b32_e32 v101, v100
	s_nop 1
	v_permlane16_swap_b32_e32 v100, v101
	s_waitcnt lgkmcnt(0)
	v_max_f32_e32 v101, v101, v101
	v_max_f32_e32 v100, v100, v101
	v_mov_b32_e32 v101, v100
	s_nop 1
	v_permlane32_swap_b32_e32 v100, v101
	v_max_f32_e32 v101, v101, v101
	v_max_f32_e32 v100, v100, v100
	v_max_f32_e32 v100, v100, v101
	v_mul_f32_e32 v100, 0x3e38aa3b, v100
	v_add_f32_e32 v101, 0x41000000, v98
	v_cmp_gt_f32_e32 vcc, v100, v101
	s_cbranch_vccz .LBB0_381
	s_nop 0
	v_cndmask_b32_e32 v100, v98, v100, vcc
	v_sub_f32_e32 v98, v98, v100
	v_exp_f32_e32 v98, v98
	v_mov_b32_e32 v101, v99
	v_mul_f32_e32 v96, v96, v98
	v_pk_mul_f32 v[46:47], v[46:47], v[98:99] op_sel_hi:[1,0]
	v_pk_mul_f32 v[44:45], v[44:45], v[98:99] op_sel_hi:[1,0]
	v_pk_mul_f32 v[38:39], v[38:39], v[98:99] op_sel_hi:[1,0]
	v_pk_mul_f32 v[36:37], v[36:37], v[98:99] op_sel_hi:[1,0]
	v_pk_mul_f32 v[42:43], v[42:43], v[98:99] op_sel_hi:[1,0]
	v_pk_mul_f32 v[40:41], v[40:41], v[98:99] op_sel_hi:[1,0]
	v_pk_mul_f32 v[34:35], v[34:35], v[98:99] op_sel_hi:[1,0]
	v_pk_mul_f32 v[32:33], v[32:33], v[98:99] op_sel_hi:[1,0]
	v_mov_b64_e32 v[98:99], v[100:101]
	s_branch .LBB0_382

.LBB0_383:
	s_cmp_lt_i32 s62, 0
	s_cbranch_scc1 .LBB0_388
	s_nop 1
	v_mfma_f32_16x16x32_bf16 v[106:109], v[56:59], v[24:27], 0
	v_mfma_f32_16x16x32_bf16 v[106:109], v[60:63], v[28:31], v[106:109]
	s_nop 7
	v_subrev_u32_e32 v56, 48, v103
	v_cmp_gt_u32_e32 vcc, s16, v56
	v_cmp_lt_i32_e64 s[46:47], -1, v105
	v_add_u32_e32 v57, 0xffffff50, v103
	s_and_b64 vcc, s[46:47], vcc
	v_cndmask_b32_e32 v56, v245, v106, vcc
	v_cmp_lt_u32_e32 vcc, s17, v57
	v_cmp_lt_i32_e64 s[46:47], -2, v105
	s_and_b64 vcc, s[46:47], vcc
	v_subrev_u32_e32 v58, 46, v103
	v_cndmask_b32_e32 v57, v245, v107, vcc
	v_cmp_gt_u32_e32 vcc, s16, v58
	v_cmp_lt_i32_e64 s[46:47], -3, v105
	s_and_b64 vcc, s[46:47], vcc
	v_subrev_u32_e32 v59, 45, v103
	v_cndmask_b32_e32 v58, v245, v108, vcc
	v_cmp_gt_u32_e32 vcc, s16, v59
	v_cmp_lt_i32_e64 s[46:47], -4, v105
	s_and_b64 vcc, s[46:47], vcc
	v_cndmask_b32_e32 v59, v245, v109, vcc
	v_max_f32_e32 v60, v59, v59
	v_max_f32_e32 v61, v58, v58
	v_max_f32_e32 v60, v61, v60
	v_max3_f32 v60, v56, v57, v60
	v_mov_b32_e32 v61, v60
	s_nop 1
	v_permlane16_swap_b32_e32 v60, v61
	s_waitcnt lgkmcnt(0)
	v_max_f32_e32 v61, v61, v61
	v_max_f32_e32 v60, v60, v61
	v_mov_b32_e32 v61, v60
	s_nop 1
	v_permlane32_swap_b32_e32 v60, v61
	v_max_f32_e32 v61, v61, v61
	v_max_f32_e32 v60, v60, v60
	v_max_f32_e32 v60, v60, v61
	v_mul_f32_e32 v60, 0x3e38aa3b, v60
	v_add_f32_e32 v61, 0x41000000, v99
	v_cmp_gt_f32_e32 vcc, v60, v61
	s_cbranch_vccz .LBB0_386
	s_nop 0
	v_cndmask_b32_e32 v60, v99, v60, vcc
	v_sub_f32_e32 v61, v99, v60
	v_exp_f32_e32 v62, v61
	v_mov_b32_e32 v99, v60
	v_mul_f32_e32 v97, v97, v62
	v_pk_mul_f32 v[18:19], v[18:19], v[62:63] op_sel_hi:[1,0]
	v_pk_mul_f32 v[16:17], v[16:17], v[62:63] op_sel_hi:[1,0]
	v_pk_mul_f32 v[10:11], v[10:11], v[62:63] op_sel_hi:[1,0]
	v_pk_mul_f32 v[8:9], v[8:9], v[62:63] op_sel_hi:[1,0]
	v_pk_mul_f32 v[6:7], v[6:7], v[62:63] op_sel_hi:[1,0]
	v_pk_mul_f32 v[4:5], v[4:5], v[62:63] op_sel_hi:[1,0]
	v_pk_mul_f32 v[2:3], v[2:3], v[62:63] op_sel_hi:[1,0]
	v_pk_mul_f32 v[0:1], v[0:1], v[62:63] op_sel_hi:[1,0]
	s_branch .LBB0_387

.LBB0_388:
	s_min_i32 s0, s62, 5
	s_lshl_b32 s0, s0, 4
	s_add_i32 s0, s60, s0
	v_or_b32_e32 v56, s0, v149
	v_med3_i32 v56, v56, 0, v244
	v_add_u32_e32 v57, s0, v194
	v_med3_i32 v57, v57, 0, v244
	v_mul_u32_u24_e32 v176, 0x2800, v56
	v_lshl_add_u64 v[60:61], v[164:165], 0, v[176:177]
	v_mul_u32_u24_e32 v176, 0x2800, v57
	s_waitcnt vmcnt(8) lgkmcnt(1)
	v_lshl_add_u64 v[84:85], v[166:167], 0, v[176:177]
	global_load_dwordx4 v[56:59], v[60:61], off offset:1536
	s_nop 0
	global_load_dwordx4 v[60:63], v[60:61], off offset:1600
	s_nop 0
	global_load_dwordx4 v[80:83], v[84:85], off offset:3088
	s_waitcnt lgkmcnt(0)
	global_load_dwordx4 v[84:87], v[84:85], off offset:3072
	s_and_b64 vcc, exec, s[44:45]
	s_cbranch_vccnz .LBB0_399
	s_waitcnt vmcnt(8)
	ds_write_b128 v211, v[92:95]
	ds_write_b128 v211, v[88:91] offset:16
	ds_read_b64_tr_b16 v[88:89], v212
	ds_read_b64_tr_b16 v[90:91], v212 offset:32
	ds_read_b64_tr_b16 v[92:93], v212 offset:64
	ds_read_b64_tr_b16 v[94:95], v212 offset:96
	v_add_u32_e32 v104, 0xffffff70, v104
	s_cmp_eq_u32 s63, 4
	v_cmp_lt_i32_e64 s[48:49], -1, v104
	v_cmp_lt_i32_e64 s[46:47], -2, v104
	v_cmp_lt_i32_e64 s[44:45], -3, v104
	v_cmp_lt_i32_e32 vcc, -4, v104
	s_cbranch_scc1 .LBB0_394
	v_add_u32_e32 v101, -16, v103
	v_cmp_gt_u32_e64 s[50:51], s16, v101
	v_add_u32_e32 v100, 0xffffff70, v103
	s_and_b64 s[48:49], s[48:49], s[50:51]
	s_nop 1
	v_mfma_f32_16x16x32_bf16 v[106:109], v[64:67], v[12:15], 0
	v_mfma_f32_16x16x32_bf16 v[106:109], v[68:71], v[20:23], v[106:109]
	s_nop 7
	s_nop 0
	v_cndmask_b32_e64 v105, v245, v106, s[48:49]
	v_cmp_lt_u32_e64 s[48:49], s17, v100
	s_and_b64 s[46:47], s[46:47], s[48:49]
	v_add_u32_e32 v100, -14, v103
	v_cndmask_b32_e64 v106, v245, v107, s[46:47]
	v_cmp_gt_u32_e64 s[46:47], s16, v100
	s_and_b64 s[44:45], s[44:45], s[46:47]
	v_add_u32_e32 v100, -13, v103
	v_cndmask_b32_e64 v107, v245, v108, s[44:45]
	v_cmp_gt_u32_e64 s[44:45], s16, v100
	s_and_b64 vcc, vcc, s[44:45]
	v_cndmask_b32_e32 v108, v245, v109, vcc
	v_max_f32_e32 v100, v108, v108
	v_max_f32_e32 v101, v107, v107
	v_max_f32_e32 v100, v101, v100
	v_max3_f32 v100, v105, v106, v100
	v_mov_b32_e32 v101, v100
	s_nop 1
	v_permlane16_swap_b32_e32 v100, v101
	s_waitcnt lgkmcnt(0)
	v_max_f32_e32 v101, v101, v101
	v_max_f32_e32 v100, v100, v101
	v_mov_b32_e32 v101, v100
	s_nop 1
	v_permlane32_swap_b32_e32 v100, v101
	v_max_f32_e32 v101, v101, v101
	v_max_f32_e32 v100, v100, v100
	v_max_f32_e32 v100, v100, v101
	v_mul_f32_e32 v100, 0x3e38aa3b, v100
	v_add_f32_e32 v101, 0x41000000, v98
	v_cmp_gt_f32_e32 vcc, v100, v101
	s_cbranch_vccz .LBB0_392
	s_nop 0
	v_cndmask_b32_e32 v100, v98, v100, vcc
	v_sub_f32_e32 v98, v98, v100
	v_exp_f32_e32 v98, v98
	v_mov_b32_e32 v101, v99
	v_mul_f32_e32 v96, v96, v98
	v_pk_mul_f32 v[46:47], v[46:47], v[98:99] op_sel_hi:[1,0]
	v_pk_mul_f32 v[44:45], v[44:45], v[98:99] op_sel_hi:[1,0]
	v_pk_mul_f32 v[38:39], v[38:39], v[98:99] op_sel_hi:[1,0]
	v_pk_mul_f32 v[36:37], v[36:37], v[98:99] op_sel_hi:[1,0]
	v_pk_mul_f32 v[42:43], v[42:43], v[98:99] op_sel_hi:[1,0]
	v_pk_mul_f32 v[40:41], v[40:41], v[98:99] op_sel_hi:[1,0]
	v_pk_mul_f32 v[34:35], v[34:35], v[98:99] op_sel_hi:[1,0]
	v_pk_mul_f32 v[32:33], v[32:33], v[98:99] op_sel_hi:[1,0]
	v_mov_b64_e32 v[98:99], v[100:101]
	s_branch .LBB0_393

.LBB0_394:
	s_cmp_lt_i32 s62, -1
	s_cbranch_scc1 .LBB0_399
	s_nop 1
	v_mfma_f32_16x16x32_bf16 v[106:109], v[64:67], v[24:27], 0
	v_mfma_f32_16x16x32_bf16 v[106:109], v[68:71], v[28:31], v[106:109]
	s_nop 7
	v_subrev_u32_e32 v64, 32, v103
	v_cmp_gt_u32_e32 vcc, s16, v64
	v_cmp_lt_i32_e64 s[44:45], -1, v104
	v_add_u32_e32 v65, 0xffffff60, v103
	s_and_b64 vcc, s[44:45], vcc
	v_cndmask_b32_e32 v64, v245, v106, vcc
	v_cmp_lt_u32_e32 vcc, s17, v65
	v_cmp_lt_i32_e64 s[44:45], -2, v104
	s_and_b64 vcc, s[44:45], vcc
	v_subrev_u32_e32 v66, 30, v103
	v_cndmask_b32_e32 v65, v245, v107, vcc
	v_cmp_gt_u32_e32 vcc, s16, v66
	v_cmp_lt_i32_e64 s[44:45], -3, v104
	s_and_b64 vcc, s[44:45], vcc
	v_subrev_u32_e32 v67, 29, v103
	v_cndmask_b32_e32 v66, v245, v108, vcc
	v_cmp_gt_u32_e32 vcc, s16, v67
	v_cmp_lt_i32_e64 s[44:45], -4, v104
	s_and_b64 vcc, s[44:45], vcc
	v_cndmask_b32_e32 v67, v245, v109, vcc
	v_max_f32_e32 v68, v67, v67
	v_max_f32_e32 v69, v66, v66
	v_max_f32_e32 v68, v69, v68
	v_max3_f32 v68, v64, v65, v68
	v_mov_b32_e32 v69, v68
	s_nop 1
	v_permlane16_swap_b32_e32 v68, v69
	s_waitcnt lgkmcnt(0)
	v_max_f32_e32 v69, v69, v69
	v_max_f32_e32 v68, v68, v69
	v_mov_b32_e32 v69, v68
	s_nop 1
	v_permlane32_swap_b32_e32 v68, v69
	v_max_f32_e32 v69, v69, v69
	v_max_f32_e32 v68, v68, v68
	v_max_f32_e32 v68, v68, v69
	v_mul_f32_e32 v68, 0x3e38aa3b, v68
	v_add_f32_e32 v69, 0x41000000, v99
	v_cmp_gt_f32_e32 vcc, v68, v69
	s_cbranch_vccz .LBB0_397
	s_nop 0
	v_cndmask_b32_e32 v68, v99, v68, vcc
	v_sub_f32_e32 v69, v99, v68
	v_exp_f32_e32 v70, v69
	v_mov_b32_e32 v99, v68
	v_mul_f32_e32 v97, v97, v70
	v_pk_mul_f32 v[18:19], v[18:19], v[70:71] op_sel_hi:[1,0]
	v_pk_mul_f32 v[16:17], v[16:17], v[70:71] op_sel_hi:[1,0]
	v_pk_mul_f32 v[10:11], v[10:11], v[70:71] op_sel_hi:[1,0]
	v_pk_mul_f32 v[8:9], v[8:9], v[70:71] op_sel_hi:[1,0]
	v_pk_mul_f32 v[6:7], v[6:7], v[70:71] op_sel_hi:[1,0]
	v_pk_mul_f32 v[4:5], v[4:5], v[70:71] op_sel_hi:[1,0]
	v_pk_mul_f32 v[2:3], v[2:3], v[70:71] op_sel_hi:[1,0]
	v_pk_mul_f32 v[0:1], v[0:1], v[70:71] op_sel_hi:[1,0]
	s_branch .LBB0_398

.LBB0_407:
	s_cmp_gt_u32 s62, 7
	s_cselect_b64 s[0:1], -1, 0
	s_add_i32 s38, s64, -16
	s_cmp_lt_u32 s62, 8
	s_cselect_b64 s[52:53], -1, 0
	s_and_b64 s[4:5], s[52:53], exec
	s_cselect_b32 s4, s38, 0x90
	s_add_i32 s4, s4, s61
	s_waitcnt vmcnt(11)
	v_or_b32_e32 v48, s4, v149
	v_lshl_add_u32 v48, v48, 2, s8
	v_add_u32_e32 v49, s4, v194
	v_med3_i32 v48, v48, 0, v244
	v_lshl_add_u32 v49, v49, 2, s8
	v_med3_i32 v49, v49, 0, v244
	v_mul_u32_u24_e32 v176, 0x2800, v48
	s_waitcnt vmcnt(10)
	v_lshl_add_u64 v[52:53], v[164:165], 0, v[176:177]
	v_mul_u32_u24_e32 v176, 0x2800, v49
	s_waitcnt vmcnt(8)
	v_lshl_add_u64 v[96:97], v[166:167], 0, v[176:177]
	global_load_dwordx4 v[48:51], v[52:53], off offset:2048
	s_nop 0
	global_load_dwordx4 v[52:55], v[52:53], off offset:2112
	s_nop 0
	global_load_dwordx4 v[92:95], v[96:97], off offset:3600
	s_nop 0
	global_load_dwordx4 v[96:99], v[96:97], off offset:3584
	s_waitcnt vmcnt(6)
	ds_write_b128 v211, v[60:63]
	ds_write_b128 v211, v[56:59] offset:16
	ds_read_b64_tr_b16 v[56:57], v212
	ds_read_b64_tr_b16 v[58:59], v212 offset:32
	ds_read_b64_tr_b16 v[60:61], v212 offset:64
	ds_read_b64_tr_b16 v[62:63], v212 offset:96
	v_add_u32_e32 v172, s64, v155
	v_add_u32_e32 v112, 0xffffff50, v172
	s_cmpk_lg_i32 s64, 0xc0
	s_cselect_b64 s[4:5], -1, 0
	s_cmpk_eq_i32 s64, 0xc0
	v_cmp_lt_i32_e64 s[48:49], -1, v112
	v_cmp_lt_i32_e64 s[46:47], -2, v112
	v_cmp_lt_i32_e64 s[44:45], -3, v112
	v_cmp_lt_i32_e32 vcc, -4, v112
	v_add_u32_e32 v213, s64, v200
	s_cbranch_scc1 .LBB0_412
	v_add_u32_e32 v88, s64, v200
	v_subrev_u32_e32 v90, 48, v88
	v_cmp_gt_u32_e64 s[50:51], s16, v90
	v_add_u32_e32 v89, 0xffffff50, v88
	s_and_b64 s[48:49], s[48:49], s[50:51]
	s_waitcnt vmcnt(4)
	s_nop 1
	v_mfma_f32_16x16x32_bf16 v[100:103], v[44:47], v[16:19], 0
	v_mfma_f32_16x16x32_bf16 v[100:103], v[40:43], v[20:23], v[100:103]
	s_nop 7
	s_nop 0
	v_cndmask_b32_e64 v90, v245, v100, s[48:49]
	v_cmp_lt_u32_e64 s[48:49], s17, v89
	s_and_b64 s[46:47], s[46:47], s[48:49]
	v_subrev_u32_e32 v89, 46, v88
	v_cndmask_b32_e64 v91, v245, v101, s[46:47]
	v_cmp_gt_u32_e64 s[46:47], s16, v89
	s_and_b64 s[44:45], s[44:45], s[46:47]
	v_subrev_u32_e32 v88, 45, v88
	v_cndmask_b32_e64 v100, v245, v102, s[44:45]
	v_cmp_gt_u32_e64 s[44:45], s16, v88
	s_and_b64 vcc, vcc, s[44:45]
	v_cndmask_b32_e32 v101, v245, v103, vcc
	v_max_f32_e32 v88, v101, v101
	v_max_f32_e32 v89, v100, v100
	v_max_f32_e32 v88, v89, v88
	v_max3_f32 v88, v90, v91, v88
	v_mov_b32_e32 v89, v88
	s_nop 1
	v_permlane16_swap_b32_e32 v88, v89
	s_waitcnt lgkmcnt(0)
	v_max_f32_e32 v89, v89, v89
	v_max_f32_e32 v88, v88, v89
	v_mov_b32_e32 v89, v88
	s_nop 1
	v_permlane32_swap_b32_e32 v88, v89
	v_max_f32_e32 v89, v89, v89
	v_max_f32_e32 v88, v88, v88
	v_max_f32_e32 v88, v88, v89
	v_mul_f32_e32 v88, 0x3e38aa3b, v88
	v_add_f32_e32 v89, 0x41000000, v168
	v_cmp_gt_f32_e32 vcc, v88, v89
	s_cbranch_vccz .LBB0_410
	s_nop 0
	v_cndmask_b32_e32 v88, v168, v88, vcc
	v_sub_f32_e32 v89, v168, v88
	v_exp_f32_e32 v102, v89
	v_mov_b32_e32 v89, v169
	v_mov_b64_e32 v[168:169], v[88:89]
	v_mul_f32_e32 v170, v170, v102
	v_pk_mul_f32 v[86:87], v[86:87], v[102:103] op_sel_hi:[1,0]
	v_pk_mul_f32 v[84:85], v[84:85], v[102:103] op_sel_hi:[1,0]
	v_pk_mul_f32 v[82:83], v[82:83], v[102:103] op_sel_hi:[1,0]
	v_pk_mul_f32 v[80:81], v[80:81], v[102:103] op_sel_hi:[1,0]
	v_pk_mul_f32 v[78:79], v[78:79], v[102:103] op_sel_hi:[1,0]
	v_pk_mul_f32 v[76:77], v[76:77], v[102:103] op_sel_hi:[1,0]
	v_pk_mul_f32 v[74:75], v[74:75], v[102:103] op_sel_hi:[1,0]
	v_pk_mul_f32 v[72:73], v[72:73], v[102:103] op_sel_hi:[1,0]
	s_branch .LBB0_411

.LBB0_412:
	s_cmp_eq_u32 s64, 48
	s_cbranch_scc1 .LBB0_417
	s_waitcnt vmcnt(4)
	s_nop 1
	v_mfma_f32_16x16x32_bf16 v[114:117], v[44:47], v[24:27], 0
	v_mfma_f32_16x16x32_bf16 v[114:117], v[40:43], v[28:31], v[114:117]
	s_nop 7
	v_add_u32_e32 v43, s64, v200
	v_subrev_u32_e32 v40, 64, v43
	v_cmp_gt_u32_e32 vcc, s16, v40
	v_cmp_lt_i32_e64 s[44:45], -1, v112
	v_add_u32_e32 v41, 0xffffff40, v43
	s_and_b64 vcc, s[44:45], vcc
	v_cndmask_b32_e32 v40, v245, v114, vcc
	v_cmp_lt_u32_e32 vcc, s17, v41
	v_cmp_lt_i32_e64 s[44:45], -2, v112
	s_and_b64 vcc, s[44:45], vcc
	v_subrev_u32_e32 v42, 62, v43
	v_cndmask_b32_e32 v41, v245, v115, vcc
	v_cmp_gt_u32_e32 vcc, s16, v42
	v_cmp_lt_i32_e64 s[44:45], -3, v112
	s_and_b64 vcc, s[44:45], vcc
	v_subrev_u32_e32 v43, 61, v43
	v_cndmask_b32_e32 v42, v245, v116, vcc
	v_cmp_gt_u32_e32 vcc, s16, v43
	v_cmp_lt_i32_e64 s[44:45], -4, v112
	s_and_b64 vcc, s[44:45], vcc
	v_cndmask_b32_e32 v43, v245, v117, vcc
	v_max_f32_e32 v44, v43, v43
	v_max_f32_e32 v45, v42, v42
	v_max_f32_e32 v44, v45, v44
	v_max3_f32 v44, v40, v41, v44
	v_mov_b32_e32 v45, v44
	s_nop 1
	v_permlane16_swap_b32_e32 v44, v45
	s_waitcnt lgkmcnt(0)
	v_max_f32_e32 v45, v45, v45
	v_max_f32_e32 v44, v44, v45
	v_mov_b32_e32 v45, v44
	s_nop 1
	v_permlane32_swap_b32_e32 v44, v45
	v_max_f32_e32 v45, v45, v45
	v_max_f32_e32 v44, v44, v44
	v_max_f32_e32 v44, v44, v45
	v_mul_f32_e32 v44, 0x3e38aa3b, v44
	v_add_f32_e32 v45, 0x41000000, v169
	v_cmp_gt_f32_e32 vcc, v44, v45
	s_cbranch_vccz .LBB0_415
	s_nop 0
	v_cndmask_b32_e32 v44, v169, v44, vcc
	v_sub_f32_e32 v45, v169, v44
	v_exp_f32_e32 v46, v45
	v_mov_b32_e32 v169, v44
	v_mul_f32_e32 v171, v171, v46
	v_pk_mul_f32 v[14:15], v[14:15], v[46:47] op_sel_hi:[1,0]
	v_pk_mul_f32 v[12:13], v[12:13], v[46:47] op_sel_hi:[1,0]
	v_pk_mul_f32 v[10:11], v[10:11], v[46:47] op_sel_hi:[1,0]
	v_pk_mul_f32 v[8:9], v[8:9], v[46:47] op_sel_hi:[1,0]
	v_pk_mul_f32 v[6:7], v[6:7], v[46:47] op_sel_hi:[1,0]
	v_pk_mul_f32 v[4:5], v[4:5], v[46:47] op_sel_hi:[1,0]
	v_pk_mul_f32 v[2:3], v[2:3], v[46:47] op_sel_hi:[1,0]
	v_pk_mul_f32 v[0:1], v[0:1], v[46:47] op_sel_hi:[1,0]
	s_branch .LBB0_416

.LBB0_420:
	v_add_u32_e32 v174, 0xffffff60, v172
	s_andn2_b64 vcc, exec, s[0:1]
	v_cmp_lt_i32_e64 s[50:51], -1, v174
	v_cmp_lt_i32_e64 s[48:49], -2, v174
	v_cmp_lt_i32_e64 s[46:47], -3, v174
	v_cmp_lt_i32_e64 s[44:45], -4, v174
	s_cbranch_vccnz .LBB0_424
	v_add_u32_e32 v173, s64, v200
	v_subrev_u32_e32 v89, 32, v173
	v_cmp_gt_u32_e32 vcc, s16, v89
	v_add_u32_e32 v88, 0xffffff60, v173
	s_and_b64 vcc, s[50:51], vcc
	s_nop 1
	v_mfma_f32_16x16x32_bf16 v[100:103], v[32:35], v[16:19], 0
	v_mfma_f32_16x16x32_bf16 v[100:103], v[36:39], v[20:23], v[100:103]
	s_nop 7
	s_nop 0
	v_cndmask_b32_e32 v90, v245, v100, vcc
	v_cmp_lt_u32_e32 vcc, s17, v88
	s_and_b64 vcc, s[48:49], vcc
	v_subrev_u32_e32 v88, 30, v173
	v_cndmask_b32_e32 v91, v245, v101, vcc
	v_cmp_gt_u32_e32 vcc, s16, v88
	s_and_b64 vcc, s[46:47], vcc
	v_subrev_u32_e32 v88, 29, v173
	v_cndmask_b32_e32 v100, v245, v102, vcc
	v_cmp_gt_u32_e32 vcc, s16, v88
	s_and_b64 vcc, s[44:45], vcc
	v_max_f32_e32 v89, v100, v100
	v_cndmask_b32_e32 v101, v245, v103, vcc
	v_max_f32_e32 v88, v101, v101
	v_max_f32_e32 v88, v89, v88
	v_max3_f32 v88, v90, v91, v88
	v_mov_b32_e32 v89, v88
	s_nop 1
	v_permlane16_swap_b32_e32 v88, v89
	s_waitcnt lgkmcnt(0)
	v_max_f32_e32 v89, v89, v89
	v_max_f32_e32 v88, v88, v89
	v_mov_b32_e32 v89, v88
	s_nop 1
	v_permlane32_swap_b32_e32 v88, v89
	v_max_f32_e32 v89, v89, v89
	v_max_f32_e32 v88, v88, v88
	v_max_f32_e32 v88, v88, v89
	v_mul_f32_e32 v88, 0x3e38aa3b, v88
	v_add_f32_e32 v89, 0x41000000, v168
	v_cmp_gt_f32_e32 vcc, v88, v89
	s_cbranch_vccz .LBB0_425
	s_nop 0
	v_cndmask_b32_e32 v88, v168, v88, vcc
	v_sub_f32_e32 v89, v168, v88
	v_exp_f32_e32 v102, v89
	v_mov_b32_e32 v89, v169
	v_mov_b64_e32 v[168:169], v[88:89]
	v_mul_f32_e32 v170, v170, v102
	v_pk_mul_f32 v[86:87], v[86:87], v[102:103] op_sel_hi:[1,0]
	v_pk_mul_f32 v[84:85], v[84:85], v[102:103] op_sel_hi:[1,0]
	v_pk_mul_f32 v[82:83], v[82:83], v[102:103] op_sel_hi:[1,0]
	v_pk_mul_f32 v[80:81], v[80:81], v[102:103] op_sel_hi:[1,0]
	v_pk_mul_f32 v[78:79], v[78:79], v[102:103] op_sel_hi:[1,0]
	v_pk_mul_f32 v[76:77], v[76:77], v[102:103] op_sel_hi:[1,0]
	v_pk_mul_f32 v[74:75], v[74:75], v[102:103] op_sel_hi:[1,0]
	v_pk_mul_f32 v[72:73], v[72:73], v[102:103] op_sel_hi:[1,0]
	s_branch .LBB0_426

.LBB0_427:
	s_nop 1
	v_mfma_f32_16x16x32_bf16 v[72:75], v[32:35], v[24:27], 0
	v_mfma_f32_16x16x32_bf16 v[72:75], v[36:39], v[28:31], v[72:75]
	s_nop 7
	v_subrev_u32_e32 v32, 48, v173
	v_cmp_gt_u32_e32 vcc, s16, v32
	v_cmp_lt_i32_e64 s[44:45], -1, v174
	v_add_u32_e32 v33, 0xffffff50, v173
	s_and_b64 vcc, s[44:45], vcc
	v_cndmask_b32_e32 v32, v245, v72, vcc
	v_cmp_lt_u32_e32 vcc, s17, v33
	v_cmp_lt_i32_e64 s[44:45], -2, v174
	s_and_b64 vcc, s[44:45], vcc
	v_subrev_u32_e32 v34, 46, v173
	v_cndmask_b32_e32 v33, v245, v73, vcc
	v_cmp_gt_u32_e32 vcc, s16, v34
	v_cmp_lt_i32_e64 s[44:45], -3, v174
	s_and_b64 vcc, s[44:45], vcc
	v_subrev_u32_e32 v35, 45, v173
	v_cndmask_b32_e32 v34, v245, v74, vcc
	v_cmp_gt_u32_e32 vcc, s16, v35
	v_cmp_lt_i32_e64 s[44:45], -4, v174
	s_and_b64 vcc, s[44:45], vcc
	v_cndmask_b32_e32 v35, v245, v75, vcc
	v_max_f32_e32 v36, v35, v35
	v_max_f32_e32 v37, v34, v34
	v_max_f32_e32 v36, v37, v36
	v_max3_f32 v36, v32, v33, v36
	v_mov_b32_e32 v37, v36
	s_nop 1
	v_permlane16_swap_b32_e32 v36, v37
	s_waitcnt lgkmcnt(0)
	v_max_f32_e32 v37, v37, v37
	v_max_f32_e32 v36, v36, v37
	v_mov_b32_e32 v37, v36
	s_nop 1
	v_permlane32_swap_b32_e32 v36, v37
	v_max_f32_e32 v37, v37, v37
	v_max_f32_e32 v36, v36, v36
	v_max_f32_e32 v36, v36, v37
	v_mul_f32_e32 v36, 0x3e38aa3b, v36
	v_add_f32_e32 v37, 0x41000000, v169
	v_cmp_gt_f32_e32 vcc, v36, v37
	s_cbranch_vccz .LBB0_429
	s_nop 0
	v_cndmask_b32_e32 v36, v169, v36, vcc
	v_sub_f32_e32 v37, v169, v36
	v_exp_f32_e32 v38, v37
	v_mov_b32_e32 v169, v36
	v_mul_f32_e32 v171, v171, v38
	v_pk_mul_f32 v[14:15], v[14:15], v[38:39] op_sel_hi:[1,0]
	v_pk_mul_f32 v[12:13], v[12:13], v[38:39] op_sel_hi:[1,0]
	v_pk_mul_f32 v[10:11], v[10:11], v[38:39] op_sel_hi:[1,0]
	v_pk_mul_f32 v[8:9], v[8:9], v[38:39] op_sel_hi:[1,0]
	v_pk_mul_f32 v[6:7], v[6:7], v[38:39] op_sel_hi:[1,0]
	v_pk_mul_f32 v[4:5], v[4:5], v[38:39] op_sel_hi:[1,0]
	v_pk_mul_f32 v[2:3], v[2:3], v[38:39] op_sel_hi:[1,0]
	v_pk_mul_f32 v[0:1], v[0:1], v[38:39] op_sel_hi:[1,0]
	s_branch .LBB0_430

.LBB0_431:
	s_min_u32 s0, s62, 5
	s_lshl_b32 s0, s0, 4
	s_add_i32 s0, s63, s0
	v_or_b32_e32 v32, s0, v149
	v_lshl_add_u32 v32, v32, 2, s8
	v_add_u32_e32 v33, s0, v194
	v_med3_i32 v32, v32, 0, v244
	v_lshl_add_u32 v33, v33, 2, s8
	v_med3_i32 v33, v33, 0, v244
	v_mul_u32_u24_e32 v176, 0x2800, v32
	v_lshl_add_u64 v[36:37], v[164:165], 0, v[176:177]
	v_mul_u32_u24_e32 v176, 0x2800, v33
	s_waitcnt vmcnt(8)
	v_lshl_add_u64 v[68:69], v[166:167], 0, v[176:177]
	global_load_dwordx4 v[32:35], v[36:37], off offset:2048
	s_nop 0
	global_load_dwordx4 v[36:39], v[36:37], off offset:2112
	s_nop 0
	global_load_dwordx4 v[64:67], v[68:69], off offset:3600
	s_nop 0
	global_load_dwordx4 v[68:71], v[68:69], off offset:3584
	s_andn2_b64 vcc, exec, s[52:53]
	s_cbranch_vccnz .LBB0_406
	s_waitcnt vmcnt(8)
	ds_write_b128 v211, v[96:99]
	ds_write_b128 v211, v[92:95] offset:16
	ds_read_b64_tr_b16 v[92:93], v212
	ds_read_b64_tr_b16 v[94:95], v212 offset:32
	ds_read_b64_tr_b16 v[96:97], v212 offset:64
	ds_read_b64_tr_b16 v[98:99], v212 offset:96
	v_add_u32_e32 v176, 0xffffff70, v172
	s_mov_b64 s[0:1], -1
	s_cmpk_lg_i32 s64, 0xa0
	v_cmp_lt_i32_e64 s[48:49], -1, v176
	v_cmp_lt_i32_e64 s[46:47], -2, v176
	v_cmp_lt_i32_e64 s[44:45], -3, v176
	v_cmp_lt_i32_e32 vcc, -4, v176
	s_cbranch_scc0 .LBB0_436
	v_add_u32_e32 v214, s64, v200
	v_add_u32_e32 v73, -16, v214
	v_cmp_gt_u32_e64 s[50:51], s16, v73
	s_nop 1
	v_mfma_f32_16x16x32_bf16 v[74:77], v[48:51], v[16:19], 0
	v_mfma_f32_16x16x32_bf16 v[74:77], v[52:55], v[20:23], v[74:77]
	s_nop 7
	v_add_u32_e32 v72, 0xffffff70, v214
	s_and_b64 s[48:49], s[48:49], s[50:51]
	v_cndmask_b32_e64 v74, v245, v74, s[48:49]
	v_cmp_lt_u32_e64 s[48:49], s17, v72
	s_and_b64 s[46:47], s[46:47], s[48:49]
	v_add_u32_e32 v72, -14, v214
	v_cndmask_b32_e64 v75, v245, v75, s[46:47]
	v_cmp_gt_u32_e64 s[46:47], s16, v72
	s_and_b64 s[44:45], s[44:45], s[46:47]
	v_add_u32_e32 v72, -13, v214
	v_cndmask_b32_e64 v76, v245, v76, s[44:45]
	v_cmp_gt_u32_e64 s[44:45], s16, v72
	s_and_b64 vcc, vcc, s[44:45]
	v_cndmask_b32_e32 v77, v245, v77, vcc
	v_max_f32_e32 v72, v77, v77
	v_max_f32_e32 v73, v76, v76
	v_max_f32_e32 v72, v73, v72
	v_max3_f32 v72, v74, v75, v72
	v_mov_b32_e32 v73, v72
	v_mov_b64_e32 v[100:101], v[124:125]
	v_mov_b64_e32 v[104:105], v[120:121]
	v_mov_b64_e32 v[88:89], v[116:117]
	v_mov_b64_e32 v[108:109], v[112:113]
	s_nop 1
	v_permlane16_swap_b32_e32 v72, v73
	s_waitcnt lgkmcnt(0)
	v_max_f32_e32 v73, v73, v73
	v_max_f32_e32 v72, v72, v73
	v_mov_b32_e32 v73, v72
	s_nop 1
	v_permlane32_swap_b32_e32 v72, v73
	v_max_f32_e32 v73, v73, v73
	v_max_f32_e32 v72, v72, v72
	v_max_f32_e32 v72, v72, v73
	v_mul_f32_e32 v79, 0x3e38aa3b, v72
	v_add_f32_e32 v72, 0x41000000, v168
	v_cmp_gt_f32_e32 vcc, v79, v72
	v_mov_b64_e32 v[102:103], v[126:127]
	v_mov_b64_e32 v[106:107], v[122:123]
	v_mov_b64_e32 v[90:91], v[118:119]
	v_mov_b64_e32 v[110:111], v[114:115]
	v_mov_b64_e32 v[72:73], v[170:171]
	v_mov_b64_e32 v[172:173], v[168:169]
	v_mov_b32_e32 v78, v168
	s_cbranch_vccz .LBB0_435
	v_cndmask_b32_e32 v172, v168, v79, vcc
	v_sub_f32_e32 v72, v168, v172
	v_exp_f32_e32 v78, v72
	v_mov_b32_e32 v173, v169
	v_mov_b32_e32 v73, v171
	v_mul_f32_e32 v72, v170, v78
	v_pk_mul_f32 v[110:111], v[114:115], v[78:79] op_sel_hi:[1,0]
	v_pk_mul_f32 v[108:109], v[112:113], v[78:79] op_sel_hi:[1,0]
	v_pk_mul_f32 v[90:91], v[118:119], v[78:79] op_sel_hi:[1,0]
	v_pk_mul_f32 v[88:89], v[116:117], v[78:79] op_sel_hi:[1,0]
	v_pk_mul_f32 v[106:107], v[122:123], v[78:79] op_sel_hi:[1,0]
	v_pk_mul_f32 v[104:105], v[120:121], v[78:79] op_sel_hi:[1,0]
	v_pk_mul_f32 v[102:103], v[126:127], v[78:79] op_sel_hi:[1,0]
	v_pk_mul_f32 v[100:101], v[124:125], v[78:79] op_sel_hi:[1,0]
	v_mov_b32_e32 v78, v172

.LBB0_438:
	s_nop 1
	v_mfma_f32_16x16x32_bf16 v[112:115], v[48:51], v[24:27], 0
	v_mfma_f32_16x16x32_bf16 v[112:115], v[52:55], v[28:31], v[112:115]
	s_nop 7
	v_subrev_u32_e32 v48, 32, v214
	v_cmp_gt_u32_e32 vcc, s16, v48
	v_cmp_lt_i32_e64 s[44:45], -1, v176
	v_add_u32_e32 v49, 0xffffff60, v214
	s_and_b64 vcc, s[44:45], vcc
	v_cndmask_b32_e32 v48, v245, v112, vcc
	v_cmp_lt_u32_e32 vcc, s17, v49
	v_cmp_lt_i32_e64 s[44:45], -2, v176
	s_and_b64 vcc, s[44:45], vcc
	v_subrev_u32_e32 v50, 30, v214
	v_cndmask_b32_e32 v49, v245, v113, vcc
	v_cmp_gt_u32_e32 vcc, s16, v50
	v_cmp_lt_i32_e64 s[44:45], -3, v176
	s_and_b64 vcc, s[44:45], vcc
	v_subrev_u32_e32 v51, 29, v214
	v_cndmask_b32_e32 v50, v245, v114, vcc
	v_cmp_gt_u32_e32 vcc, s16, v51
	v_cmp_lt_i32_e64 s[44:45], -4, v176
	s_and_b64 vcc, s[44:45], vcc
	v_cndmask_b32_e32 v51, v245, v115, vcc
	v_max_f32_e32 v52, v51, v51
	v_max_f32_e32 v53, v50, v50
	v_max_f32_e32 v52, v53, v52
	v_max3_f32 v52, v48, v49, v52
	v_mov_b32_e32 v53, v52
	s_nop 1
	v_permlane16_swap_b32_e32 v52, v53
	s_waitcnt lgkmcnt(0)
	v_max_f32_e32 v53, v53, v53
	v_max_f32_e32 v52, v52, v53
	v_mov_b32_e32 v53, v52
	s_nop 1
	v_permlane32_swap_b32_e32 v52, v53
	v_max_f32_e32 v53, v53, v53
	v_max_f32_e32 v52, v52, v52
	v_max_f32_e32 v52, v52, v53
	v_mul_f32_e32 v52, 0x3e38aa3b, v52
	v_add_f32_e32 v53, 0x41000000, v173
	v_cmp_gt_f32_e32 vcc, v52, v53
	s_cbranch_vccz .LBB0_440
	s_nop 0
	v_cndmask_b32_e32 v52, v173, v52, vcc
	v_sub_f32_e32 v53, v173, v52
	v_exp_f32_e32 v54, v53
	v_mov_b32_e32 v173, v52
	v_mul_f32_e32 v175, v175, v54
	v_pk_mul_f32 v[14:15], v[14:15], v[54:55] op_sel_hi:[1,0]
	v_pk_mul_f32 v[12:13], v[12:13], v[54:55] op_sel_hi:[1,0]
	v_pk_mul_f32 v[10:11], v[10:11], v[54:55] op_sel_hi:[1,0]
	v_pk_mul_f32 v[8:9], v[8:9], v[54:55] op_sel_hi:[1,0]
	v_pk_mul_f32 v[6:7], v[6:7], v[54:55] op_sel_hi:[1,0]
	v_pk_mul_f32 v[4:5], v[4:5], v[54:55] op_sel_hi:[1,0]
	v_pk_mul_f32 v[2:3], v[2:3], v[54:55] op_sel_hi:[1,0]
	v_pk_mul_f32 v[0:1], v[0:1], v[54:55] op_sel_hi:[1,0]
	s_branch .LBB0_441

.LBB0_448:
	s_add_i32 s47, s4, s39
	s_add_i32 s0, s47, 0xa0
	s_cmp_lt_u32 s46, 7
	s_cselect_b32 s0, s0, 0x80
	s_add_i32 s0, s0, s5
	v_or_b32_e32 v52, s0, v149
	v_lshl_add_u32 v52, v52, 4, s9
	v_add_u32_e32 v53, s0, v194
	v_med3_i32 v52, v52, 0, v244
	v_lshl_add_u32 v53, v53, 4, s9
	v_med3_i32 v53, v53, 0, v244
	v_mul_u32_u24_e32 v176, 0x2800, v52
	v_lshl_add_u64 v[56:57], v[72:73], 0, v[176:177]
	v_mul_u32_u24_e32 v176, 0x2800, v53
	v_lshl_add_u64 v[64:65], v[74:75], 0, v[176:177]
	global_load_dwordx4 v[52:55], v[56:57], off offset:2560
	s_nop 0
	global_load_dwordx4 v[56:59], v[56:57], off offset:2624
	s_nop 0
	global_load_dwordx4 v[60:63], v[64:65], off offset:16
	s_nop 0
	global_load_dwordx4 v[64:67], v[64:65], off
	s_waitcnt vmcnt(6)
	ds_write_b128 v211, v[28:31]
	ds_write_b128 v211, v[16:19] offset:16
	v_add_u32_e32 v83, s39, v78
	ds_read_b64_tr_b16 v[16:17], v212
	ds_read_b64_tr_b16 v[18:19], v212 offset:32
	ds_read_b64_tr_b16 v[28:29], v212 offset:64
	ds_read_b64_tr_b16 v[30:31], v212 offset:96
	v_add_u32_e32 v84, s39, v195
	s_waitcnt vmcnt(4)
	s_nop 1
	v_mfma_f32_16x16x32_bf16 v[88:91], v[20:23], v[0:3], 0
	v_mfma_f32_16x16x32_bf16 v[88:91], v[24:27], v[4:7], v[88:91]
	s_nop 7
	v_add_u32_e32 v20, 0x80, v83
	v_cmp_gt_u32_e32 vcc, s16, v20
	v_cmp_lt_i32_e64 s[44:45], -1, v84
	s_and_b64 vcc, s[44:45], vcc
	v_cndmask_b32_e32 v20, v245, v88, vcc
	v_cmp_lt_u32_e32 vcc, s17, v83
	v_cmp_lt_i32_e64 s[44:45], -2, v84
	s_and_b64 vcc, s[44:45], vcc
	v_add_u32_e32 v22, 0x82, v83
	v_cndmask_b32_e32 v21, v245, v89, vcc
	v_cmp_gt_u32_e32 vcc, s16, v22
	v_cmp_lt_i32_e64 s[44:45], -3, v84
	s_and_b64 vcc, s[44:45], vcc
	v_add_u32_e32 v23, 0x83, v83
	v_cndmask_b32_e32 v22, v245, v90, vcc
	v_cmp_gt_u32_e32 vcc, s16, v23
	v_cmp_lt_i32_e64 s[44:45], -4, v84
	s_and_b64 vcc, s[44:45], vcc
	v_cndmask_b32_e32 v23, v245, v91, vcc
	v_max_f32_e32 v24, v23, v23
	v_max_f32_e32 v25, v22, v22
	v_max_f32_e32 v24, v25, v24
	v_max3_f32 v24, v20, v21, v24
	v_mov_b32_e32 v25, v24
	v_add_f32_e32 v85, 0x41000000, v82
	s_nop 1
	v_permlane16_swap_b32_e32 v24, v25
	s_waitcnt lgkmcnt(0)
	v_max_f32_e32 v25, v25, v25
	v_max_f32_e32 v24, v24, v25
	v_mov_b32_e32 v25, v24
	s_nop 1
	v_permlane32_swap_b32_e32 v24, v25
	v_max_f32_e32 v25, v25, v25
	v_max_f32_e32 v24, v24, v24
	v_max_f32_e32 v24, v24, v25
	v_mul_f32_e32 v24, 0x3e38aa3b, v24
	v_cmp_gt_f32_e32 vcc, v24, v85
	s_cbranch_vccz .LBB0_450
	s_nop 0
	v_cndmask_b32_e32 v25, v82, v24, vcc
	v_sub_f32_e32 v24, v82, v25
	v_exp_f32_e32 v24, v24
	v_add_f32_e32 v85, 0x41000000, v25
	v_mov_b32_e32 v82, v25
	v_mul_f32_e32 v86, v86, v24
	v_pk_mul_f32 v[10:11], v[10:11], v[24:25] op_sel_hi:[1,0]
	v_pk_mul_f32 v[8:9], v[8:9], v[24:25] op_sel_hi:[1,0]
	v_pk_mul_f32 v[70:71], v[70:71], v[24:25] op_sel_hi:[1,0]
	v_pk_mul_f32 v[68:69], v[68:69], v[24:25] op_sel_hi:[1,0]
	v_pk_mul_f32 v[14:15], v[14:15], v[24:25] op_sel_hi:[1,0]
	v_pk_mul_f32 v[12:13], v[12:13], v[24:25] op_sel_hi:[1,0]
	v_pk_mul_f32 v[50:51], v[50:51], v[24:25] op_sel_hi:[1,0]
	v_pk_mul_f32 v[48:49], v[48:49], v[24:25] op_sel_hi:[1,0]
.LBB0_450:
	v_fma_f32 v21, v21, s18, -v82
	v_fma_f32 v20, v20, s18, -v82
	v_exp_f32_e32 v24, v21
	v_fma_f32 v21, v22, s18, -v82
	v_fma_f32 v22, v23, s18, -v82
	s_cmp_gt_u32 s46, 5
	v_exp_f32_e32 v20, v20
	v_exp_f32_e32 v21, v21
	v_exp_f32_e32 v25, v22
	s_cselect_b64 s[0:1], -1, 0
	s_addk_i32 s47, 0xb0
	s_cmp_lt_u32 s46, 6
	s_cselect_b32 s44, s47, 0x80
	s_add_i32 s44, s44, s5
	v_pk_add_f32 v[22:23], v[20:21], v[24:25]
	v_cvt_pk_bf16_f32 v20, v20, v24
	v_cvt_pk_bf16_f32 v21, v21, v25
	s_nop 0
	s_nop 1
	v_mfma_f32_16x16x16_bf16 v[48:51], v[16:17], v[20:21], v[48:51]
	v_mfma_f32_16x16x16_bf16 v[12:15], v[18:19], v[20:21], v[12:15]
	v_mfma_f32_16x16x16_bf16 v[68:71], v[28:29], v[20:21], v[68:71]
	v_mfma_f32_16x16x16_bf16 v[8:11], v[30:31], v[20:21], v[8:11]
	s_nop 7
	v_or_b32_e32 v16, s44, v149
	v_lshl_add_u32 v16, v16, 4, s9
	v_add_u32_e32 v17, s44, v194
	v_med3_i32 v16, v16, 0, v244
	v_lshl_add_u32 v17, v17, 4, s9
	v_med3_i32 v18, v17, 0, v244
	v_mul_u32_u24_e32 v176, 0x2800, v16
	v_lshl_add_u64 v[16:17], v[72:73], 0, v[176:177]
	v_mul_u32_u24_e32 v176, 0x2800, v18
	v_add_f32_e32 v22, v22, v23
	v_lshl_add_u64 v[28:29], v[74:75], 0, v[176:177]
	v_add_f32_e32 v87, v86, v22
	global_load_dwordx4 v[20:23], v[16:17], off offset:2560
	global_load_dwordx4 v[24:27], v[16:17], off offset:2624
	s_nop 0
	global_load_dwordx4 v[16:19], v[28:29], off offset:16
	s_nop 0
	global_load_dwordx4 v[28:31], v[28:29], off
	ds_write_b128 v211, v[36:39]
	ds_write_b128 v211, v[32:35] offset:16
	ds_read_b64_tr_b16 v[32:33], v212
	ds_read_b64_tr_b16 v[34:35], v212 offset:32
	ds_read_b64_tr_b16 v[36:37], v212 offset:64
	ds_read_b64_tr_b16 v[38:39], v212 offset:96
	v_add_u32_e32 v86, 16, v84
	s_nop 1
	v_mfma_f32_16x16x32_bf16 v[88:91], v[40:43], v[0:3], 0
	v_mfma_f32_16x16x32_bf16 v[88:91], v[44:47], v[4:7], v[88:91]
	s_nop 7
	v_add_u32_e32 v40, 0x90, v83
	v_cmp_gt_u32_e32 vcc, s16, v40
	v_cmp_lt_i32_e64 s[44:45], -1, v86
	v_add_u32_e32 v41, 16, v83
	s_and_b64 vcc, s[44:45], vcc
	v_cndmask_b32_e32 v40, v245, v88, vcc
	v_cmp_lt_u32_e32 vcc, s17, v41
	v_cmp_lt_i32_e64 s[44:45], -2, v86
	s_and_b64 vcc, s[44:45], vcc
	v_add_u32_e32 v42, 0x92, v83
	v_cndmask_b32_e32 v41, v245, v89, vcc
	v_cmp_gt_u32_e32 vcc, s16, v42
	v_cmp_lt_i32_e64 s[44:45], -3, v86
	s_and_b64 vcc, s[44:45], vcc
	v_add_u32_e32 v43, 0x93, v83
	v_cndmask_b32_e32 v42, v245, v90, vcc
	v_cmp_gt_u32_e32 vcc, s16, v43
	v_cmp_lt_i32_e64 s[44:45], -4, v86
	s_and_b64 vcc, s[44:45], vcc
	v_cndmask_b32_e32 v43, v245, v91, vcc
	v_max_f32_e32 v44, v43, v43
	v_max_f32_e32 v45, v42, v42
	v_max_f32_e32 v44, v45, v44
	v_max3_f32 v44, v40, v41, v44
	v_mov_b32_e32 v45, v44
	s_nop 1
	v_permlane16_swap_b32_e32 v44, v45
	s_waitcnt lgkmcnt(0)
	v_max_f32_e32 v45, v45, v45
	v_max_f32_e32 v44, v44, v45
	v_mov_b32_e32 v45, v44
	s_nop 1
	v_permlane32_swap_b32_e32 v44, v45
	v_max_f32_e32 v45, v45, v45
	v_max_f32_e32 v44, v44, v44
	v_max_f32_e32 v44, v44, v45
	v_mul_f32_e32 v44, 0x3e38aa3b, v44
	v_cmp_gt_f32_e32 vcc, v44, v85
	s_cbranch_vccz .LBB0_452
	s_nop 0
	v_cndmask_b32_e32 v45, v82, v44, vcc
	v_sub_f32_e32 v44, v82, v45
	v_exp_f32_e32 v44, v44
	v_xor_b32_e32 v86, 0x80000000, v45
	v_add_f32_e32 v85, 0x41000000, v45
	v_mov_b32_e32 v82, v45
	v_mul_f32_e32 v87, v87, v44
	v_pk_mul_f32 v[50:51], v[50:51], v[44:45] op_sel_hi:[1,0]
	v_pk_mul_f32 v[48:49], v[48:49], v[44:45] op_sel_hi:[1,0]
	v_pk_mul_f32 v[14:15], v[14:15], v[44:45] op_sel_hi:[1,0]
	v_pk_mul_f32 v[12:13], v[12:13], v[44:45] op_sel_hi:[1,0]
	v_pk_mul_f32 v[70:71], v[70:71], v[44:45] op_sel_hi:[1,0]
	v_pk_mul_f32 v[68:69], v[68:69], v[44:45] op_sel_hi:[1,0]
	v_pk_mul_f32 v[10:11], v[10:11], v[44:45] op_sel_hi:[1,0]
	v_pk_mul_f32 v[8:9], v[8:9], v[44:45] op_sel_hi:[1,0]
	s_branch .LBB0_453

.LBB0_453:
	v_fmamk_f32 v41, v41, 0x3e38aa3b, v86
	v_fmamk_f32 v40, v40, 0x3e38aa3b, v86
	v_exp_f32_e32 v44, v41
	v_fmamk_f32 v41, v42, 0x3e38aa3b, v86
	v_fmamk_f32 v42, v43, 0x3e38aa3b, v86
	v_exp_f32_e32 v40, v40
	v_exp_f32_e32 v41, v41
	v_exp_f32_e32 v45, v42
	s_min_u32 s44, s46, 4
	s_lshl_b32 s44, s44, 4
	s_add_i32 s44, s44, s37
	v_pk_add_f32 v[42:43], v[40:41], v[44:45]
	v_cvt_pk_bf16_f32 v40, v40, v44
	v_cvt_pk_bf16_f32 v41, v41, v45
	v_add_u32_e32 v84, 32, v84
	s_nop 1
	v_mfma_f32_16x16x16_bf16 v[48:51], v[32:33], v[40:41], v[48:51]
	v_mfma_f32_16x16x16_bf16 v[12:15], v[34:35], v[40:41], v[12:15]
	v_mfma_f32_16x16x16_bf16 v[68:71], v[36:37], v[40:41], v[68:71]
	v_mfma_f32_16x16x16_bf16 v[8:11], v[38:39], v[40:41], v[8:11]
	s_nop 7
	v_or_b32_e32 v32, s44, v149
	v_lshl_add_u32 v32, v32, 4, s9
	v_add_u32_e32 v33, s44, v194
	v_med3_i32 v32, v32, 0, v244
	v_lshl_add_u32 v33, v33, 4, s9
	v_med3_i32 v34, v33, 0, v244
	v_mul_u32_u24_e32 v176, 0x2800, v32
	v_lshl_add_u64 v[32:33], v[72:73], 0, v[176:177]
	v_mul_u32_u24_e32 v176, 0x2800, v34
	v_add_f32_e32 v42, v42, v43
	v_lshl_add_u64 v[36:37], v[74:75], 0, v[176:177]
	v_add_f32_e32 v87, v87, v42
	global_load_dwordx4 v[40:43], v[32:33], off offset:2560
	global_load_dwordx4 v[44:47], v[32:33], off offset:2624
	s_nop 0
	global_load_dwordx4 v[32:35], v[36:37], off offset:16
	s_nop 0
	global_load_dwordx4 v[36:39], v[36:37], off
	s_waitcnt vmcnt(8)
	ds_write_b128 v211, v[64:67]
	ds_write_b128 v211, v[60:63] offset:16
	ds_read_b64_tr_b16 v[60:61], v212
	ds_read_b64_tr_b16 v[62:63], v212 offset:32
	ds_read_b64_tr_b16 v[64:65], v212 offset:64
	ds_read_b64_tr_b16 v[66:67], v212 offset:96
	s_nop 1
	v_mfma_f32_16x16x32_bf16 v[88:91], v[52:55], v[0:3], 0
	v_mfma_f32_16x16x32_bf16 v[88:91], v[56:59], v[4:7], v[88:91]
	s_nop 7
	v_add_u32_e32 v52, 0xa0, v83
	v_cmp_gt_u32_e32 vcc, s16, v52
	v_cmp_lt_i32_e64 s[44:45], -1, v84
	v_add_u32_e32 v53, 32, v83
	s_and_b64 vcc, s[44:45], vcc
	v_cndmask_b32_e32 v52, v245, v88, vcc
	v_cmp_lt_u32_e32 vcc, s17, v53
	v_cmp_lt_i32_e64 s[44:45], -2, v84
	s_and_b64 vcc, s[44:45], vcc
	v_add_u32_e32 v54, 0xa2, v83
	v_cndmask_b32_e32 v53, v245, v89, vcc
	v_cmp_gt_u32_e32 vcc, s16, v54
	v_cmp_lt_i32_e64 s[44:45], -3, v84
	s_and_b64 vcc, s[44:45], vcc
	v_add_u32_e32 v55, 0xa3, v83
	v_cndmask_b32_e32 v54, v245, v90, vcc
	v_cmp_gt_u32_e32 vcc, s16, v55
	v_cmp_lt_i32_e64 s[44:45], -4, v84
	s_and_b64 vcc, s[44:45], vcc
	v_cndmask_b32_e32 v55, v245, v91, vcc
	v_max_f32_e32 v56, v55, v55
	v_max_f32_e32 v57, v54, v54
	v_max_f32_e32 v56, v57, v56
	v_max3_f32 v56, v52, v53, v56
	v_mov_b32_e32 v57, v56
	s_nop 1
	v_permlane16_swap_b32_e32 v56, v57
	s_waitcnt lgkmcnt(0)
	v_max_f32_e32 v57, v57, v57
	v_max_f32_e32 v56, v56, v57
	v_mov_b32_e32 v57, v56
	s_nop 1
	v_permlane32_swap_b32_e32 v56, v57
	v_max_f32_e32 v57, v57, v57
	v_max_f32_e32 v56, v56, v56
	v_max_f32_e32 v56, v56, v57
	v_mul_f32_e32 v56, 0x3e38aa3b, v56
	v_cmp_gt_f32_e32 vcc, v56, v85
	s_cbranch_vccz .LBB0_447
	s_nop 0
	v_cndmask_b32_e32 v57, v82, v56, vcc
	v_sub_f32_e32 v56, v82, v57
	v_exp_f32_e32 v56, v56
	v_xor_b32_e32 v86, 0x80000000, v57
	v_mov_b32_e32 v82, v57
	v_mul_f32_e32 v87, v87, v56
	v_pk_mul_f32 v[50:51], v[50:51], v[56:57] op_sel_hi:[1,0]
	v_pk_mul_f32 v[48:49], v[48:49], v[56:57] op_sel_hi:[1,0]
	v_pk_mul_f32 v[14:15], v[14:15], v[56:57] op_sel_hi:[1,0]
	v_pk_mul_f32 v[12:13], v[12:13], v[56:57] op_sel_hi:[1,0]
	v_pk_mul_f32 v[70:71], v[70:71], v[56:57] op_sel_hi:[1,0]
	v_pk_mul_f32 v[68:69], v[68:69], v[56:57] op_sel_hi:[1,0]
	v_pk_mul_f32 v[10:11], v[10:11], v[56:57] op_sel_hi:[1,0]
	v_pk_mul_f32 v[8:9], v[8:9], v[56:57] op_sel_hi:[1,0]
	s_branch .LBB0_447

.LBB0_459:
	s_add_i32 s31, s4, s30
	s_add_i32 s0, s31, 0xa0
	s_cmp_lt_u32 s36, 7
	s_cselect_b32 s0, s0, 0x80
	s_add_i32 s0, s0, s5
	v_or_b32_e32 v52, s0, v149
	v_lshl_add_u32 v52, v52, 4, s10
	v_add_u32_e32 v53, s0, v194
	v_med3_i32 v52, v52, 0, v244
	v_lshl_add_u32 v53, v53, 4, s10
	v_med3_i32 v53, v53, 0, v244
	v_mul_u32_u24_e32 v176, 0x2800, v52
	v_lshl_add_u64 v[56:57], v[72:73], 0, v[176:177]
	v_mul_u32_u24_e32 v176, 0x2800, v53
	v_lshl_add_u64 v[64:65], v[74:75], 0, v[176:177]
	global_load_dwordx4 v[52:55], v[56:57], off offset:2560
	s_nop 0
	global_load_dwordx4 v[56:59], v[56:57], off offset:2624
	s_nop 0
	global_load_dwordx4 v[60:63], v[64:65], off offset:16
	s_nop 0
	global_load_dwordx4 v[64:67], v[64:65], off
	s_waitcnt vmcnt(6)
	ds_write_b128 v211, v[28:31]
	ds_write_b128 v211, v[16:19] offset:16
	v_add_u32_e32 v77, s30, v78
	ds_read_b64_tr_b16 v[16:17], v212
	ds_read_b64_tr_b16 v[18:19], v212 offset:32
	ds_read_b64_tr_b16 v[28:29], v212 offset:64
	ds_read_b64_tr_b16 v[30:31], v212 offset:96
	v_add_u32_e32 v79, s30, v195
	s_waitcnt vmcnt(4)
	s_nop 1
	v_mfma_f32_16x16x32_bf16 v[82:85], v[20:23], v[0:3], 0
	v_mfma_f32_16x16x32_bf16 v[82:85], v[24:27], v[4:7], v[82:85]
	s_nop 7
	v_add_u32_e32 v20, 0x80, v77
	v_cmp_gt_u32_e32 vcc, s16, v20
	v_cmp_lt_i32_e64 s[44:45], -1, v79
	s_and_b64 vcc, s[44:45], vcc
	v_cndmask_b32_e32 v20, v245, v82, vcc
	v_cmp_lt_u32_e32 vcc, s17, v77
	v_cmp_lt_i32_e64 s[44:45], -2, v79
	s_and_b64 vcc, s[44:45], vcc
	v_add_u32_e32 v22, 0x82, v77
	v_cndmask_b32_e32 v21, v245, v83, vcc
	v_cmp_gt_u32_e32 vcc, s16, v22
	v_cmp_lt_i32_e64 s[44:45], -3, v79
	s_and_b64 vcc, s[44:45], vcc
	v_add_u32_e32 v23, 0x83, v77
	v_cndmask_b32_e32 v22, v245, v84, vcc
	v_cmp_gt_u32_e32 vcc, s16, v23
	v_cmp_lt_i32_e64 s[44:45], -4, v79
	s_and_b64 vcc, s[44:45], vcc
	v_cndmask_b32_e32 v23, v245, v85, vcc
	v_max_f32_e32 v24, v23, v23
	v_max_f32_e32 v25, v22, v22
	v_max_f32_e32 v24, v25, v24
	v_max3_f32 v24, v20, v21, v24
	v_mov_b32_e32 v25, v24
	v_add_f32_e32 v80, 0x41000000, v76
	s_nop 1
	v_permlane16_swap_b32_e32 v24, v25
	s_waitcnt lgkmcnt(0)
	v_max_f32_e32 v25, v25, v25
	v_max_f32_e32 v24, v24, v25
	v_mov_b32_e32 v25, v24
	s_nop 1
	v_permlane32_swap_b32_e32 v24, v25
	v_max_f32_e32 v25, v25, v25
	v_max_f32_e32 v24, v24, v24
	v_max_f32_e32 v24, v24, v25
	v_mul_f32_e32 v24, 0x3e38aa3b, v24
	v_cmp_gt_f32_e32 vcc, v24, v80
	s_cbranch_vccz .LBB0_461
	s_nop 0
	v_cndmask_b32_e32 v25, v76, v24, vcc
	v_sub_f32_e32 v24, v76, v25
	v_exp_f32_e32 v24, v24
	v_add_f32_e32 v80, 0x41000000, v25
	v_mov_b32_e32 v76, v25
	v_mul_f32_e32 v81, v81, v24
	v_pk_mul_f32 v[10:11], v[10:11], v[24:25] op_sel_hi:[1,0]
	v_pk_mul_f32 v[8:9], v[8:9], v[24:25] op_sel_hi:[1,0]
	v_pk_mul_f32 v[14:15], v[14:15], v[24:25] op_sel_hi:[1,0]
	v_pk_mul_f32 v[12:13], v[12:13], v[24:25] op_sel_hi:[1,0]
	v_pk_mul_f32 v[70:71], v[70:71], v[24:25] op_sel_hi:[1,0]
	v_pk_mul_f32 v[68:69], v[68:69], v[24:25] op_sel_hi:[1,0]
	v_pk_mul_f32 v[50:51], v[50:51], v[24:25] op_sel_hi:[1,0]
	v_pk_mul_f32 v[48:49], v[48:49], v[24:25] op_sel_hi:[1,0]
.LBB0_461:
	v_fma_f32 v21, v21, s18, -v76
	v_fma_f32 v20, v20, s18, -v76
	v_exp_f32_e32 v24, v21
	v_fma_f32 v21, v22, s18, -v76
	v_fma_f32 v22, v23, s18, -v76
	s_cmp_gt_u32 s36, 5
	v_exp_f32_e32 v20, v20
	v_exp_f32_e32 v21, v21
	v_exp_f32_e32 v25, v22
	s_cselect_b64 s[0:1], -1, 0
	s_addk_i32 s31, 0xb0
	s_cmp_lt_u32 s36, 6
	s_cselect_b32 s31, s31, 0x80
	s_add_i32 s31, s31, s5
	v_pk_add_f32 v[22:23], v[20:21], v[24:25]
	v_cvt_pk_bf16_f32 v20, v20, v24
	v_cvt_pk_bf16_f32 v21, v21, v25
	s_nop 0
	s_nop 1
	v_mfma_f32_16x16x16_bf16 v[48:51], v[16:17], v[20:21], v[48:51]
	v_mfma_f32_16x16x16_bf16 v[68:71], v[18:19], v[20:21], v[68:71]
	v_mfma_f32_16x16x16_bf16 v[12:15], v[28:29], v[20:21], v[12:15]
	v_mfma_f32_16x16x16_bf16 v[8:11], v[30:31], v[20:21], v[8:11]
	s_nop 7
	v_or_b32_e32 v16, s31, v149
	v_lshl_add_u32 v16, v16, 4, s10
	v_add_u32_e32 v17, s31, v194
	v_med3_i32 v16, v16, 0, v244
	v_lshl_add_u32 v17, v17, 4, s10
	v_med3_i32 v18, v17, 0, v244
	v_mul_u32_u24_e32 v176, 0x2800, v16
	v_lshl_add_u64 v[16:17], v[72:73], 0, v[176:177]
	v_mul_u32_u24_e32 v176, 0x2800, v18
	v_add_f32_e32 v22, v22, v23
	v_lshl_add_u64 v[28:29], v[74:75], 0, v[176:177]
	v_add_f32_e32 v82, v81, v22
	global_load_dwordx4 v[20:23], v[16:17], off offset:2560
	global_load_dwordx4 v[24:27], v[16:17], off offset:2624
	s_nop 0
	global_load_dwordx4 v[16:19], v[28:29], off offset:16
	s_nop 0
	global_load_dwordx4 v[28:31], v[28:29], off
	ds_write_b128 v211, v[36:39]
	ds_write_b128 v211, v[32:35] offset:16
	ds_read_b64_tr_b16 v[32:33], v212
	ds_read_b64_tr_b16 v[34:35], v212 offset:32
	ds_read_b64_tr_b16 v[36:37], v212 offset:64
	ds_read_b64_tr_b16 v[38:39], v212 offset:96
	v_add_u32_e32 v81, 16, v79
	s_nop 1
	v_mfma_f32_16x16x32_bf16 v[84:87], v[40:43], v[0:3], 0
	v_mfma_f32_16x16x32_bf16 v[84:87], v[44:47], v[4:7], v[84:87]
	s_nop 7
	v_add_u32_e32 v40, 0x90, v77
	v_cmp_gt_u32_e32 vcc, s16, v40
	v_cmp_lt_i32_e64 s[44:45], -1, v81
	v_add_u32_e32 v41, 16, v77
	s_and_b64 vcc, s[44:45], vcc
	v_cndmask_b32_e32 v40, v245, v84, vcc
	v_cmp_lt_u32_e32 vcc, s17, v41
	v_cmp_lt_i32_e64 s[44:45], -2, v81
	s_and_b64 vcc, s[44:45], vcc
	v_add_u32_e32 v42, 0x92, v77
	v_cndmask_b32_e32 v41, v245, v85, vcc
	v_cmp_gt_u32_e32 vcc, s16, v42
	v_cmp_lt_i32_e64 s[44:45], -3, v81
	s_and_b64 vcc, s[44:45], vcc
	v_add_u32_e32 v43, 0x93, v77
	v_cndmask_b32_e32 v42, v245, v86, vcc
	v_cmp_gt_u32_e32 vcc, s16, v43
	v_cmp_lt_i32_e64 s[44:45], -4, v81
	s_and_b64 vcc, s[44:45], vcc
	v_cndmask_b32_e32 v43, v245, v87, vcc
	v_max_f32_e32 v44, v43, v43
	v_max_f32_e32 v45, v42, v42
	v_max_f32_e32 v44, v45, v44
	v_max3_f32 v44, v40, v41, v44
	v_mov_b32_e32 v45, v44
	s_nop 1
	v_permlane16_swap_b32_e32 v44, v45
	s_waitcnt lgkmcnt(0)
	v_max_f32_e32 v45, v45, v45
	v_max_f32_e32 v44, v44, v45
	v_mov_b32_e32 v45, v44
	s_nop 1
	v_permlane32_swap_b32_e32 v44, v45
	v_max_f32_e32 v45, v45, v45
	v_max_f32_e32 v44, v44, v44
	v_max_f32_e32 v44, v44, v45
	v_mul_f32_e32 v44, 0x3e38aa3b, v44
	v_cmp_gt_f32_e32 vcc, v44, v80
	s_cbranch_vccz .LBB0_463
	s_nop 0
	v_cndmask_b32_e32 v45, v76, v44, vcc
	v_sub_f32_e32 v44, v76, v45
	v_exp_f32_e32 v44, v44
	v_xor_b32_e32 v81, 0x80000000, v45
	v_add_f32_e32 v80, 0x41000000, v45
	v_mov_b32_e32 v76, v45
	v_mul_f32_e32 v82, v82, v44
	v_pk_mul_f32 v[50:51], v[50:51], v[44:45] op_sel_hi:[1,0]
	v_pk_mul_f32 v[48:49], v[48:49], v[44:45] op_sel_hi:[1,0]
	v_pk_mul_f32 v[70:71], v[70:71], v[44:45] op_sel_hi:[1,0]
	v_pk_mul_f32 v[68:69], v[68:69], v[44:45] op_sel_hi:[1,0]
	v_pk_mul_f32 v[14:15], v[14:15], v[44:45] op_sel_hi:[1,0]
	v_pk_mul_f32 v[12:13], v[12:13], v[44:45] op_sel_hi:[1,0]
	v_pk_mul_f32 v[10:11], v[10:11], v[44:45] op_sel_hi:[1,0]
	v_pk_mul_f32 v[8:9], v[8:9], v[44:45] op_sel_hi:[1,0]
	s_branch .LBB0_464

.LBB0_464:
	v_fmamk_f32 v41, v41, 0x3e38aa3b, v81
	v_fmamk_f32 v40, v40, 0x3e38aa3b, v81
	v_exp_f32_e32 v44, v41
	v_fmamk_f32 v41, v42, 0x3e38aa3b, v81
	v_fmamk_f32 v42, v43, 0x3e38aa3b, v81
	v_exp_f32_e32 v40, v40
	v_exp_f32_e32 v41, v41
	v_exp_f32_e32 v45, v42
	s_min_u32 s31, s36, 4
	s_lshl_b32 s31, s31, 4
	s_add_i32 s31, s31, s37
	v_pk_add_f32 v[42:43], v[40:41], v[44:45]
	v_cvt_pk_bf16_f32 v40, v40, v44
	v_cvt_pk_bf16_f32 v41, v41, v45
	v_add_u32_e32 v79, 32, v79
	s_nop 1
	v_mfma_f32_16x16x16_bf16 v[48:51], v[32:33], v[40:41], v[48:51]
	v_mfma_f32_16x16x16_bf16 v[68:71], v[34:35], v[40:41], v[68:71]
	v_mfma_f32_16x16x16_bf16 v[12:15], v[36:37], v[40:41], v[12:15]
	v_mfma_f32_16x16x16_bf16 v[8:11], v[38:39], v[40:41], v[8:11]
	s_nop 7
	v_or_b32_e32 v32, s31, v149
	v_lshl_add_u32 v32, v32, 4, s10
	v_add_u32_e32 v33, s31, v194
	v_med3_i32 v32, v32, 0, v244
	v_lshl_add_u32 v33, v33, 4, s10
	v_med3_i32 v34, v33, 0, v244
	v_mul_u32_u24_e32 v176, 0x2800, v32
	v_lshl_add_u64 v[32:33], v[72:73], 0, v[176:177]
	v_mul_u32_u24_e32 v176, 0x2800, v34
	v_add_f32_e32 v42, v42, v43
	v_lshl_add_u64 v[36:37], v[74:75], 0, v[176:177]
	v_add_f32_e32 v82, v82, v42
	global_load_dwordx4 v[40:43], v[32:33], off offset:2560
	global_load_dwordx4 v[44:47], v[32:33], off offset:2624
	s_nop 0
	global_load_dwordx4 v[32:35], v[36:37], off offset:16
	s_nop 0
	global_load_dwordx4 v[36:39], v[36:37], off
	s_waitcnt vmcnt(8)
	ds_write_b128 v211, v[64:67]
	ds_write_b128 v211, v[60:63] offset:16
	ds_read_b64_tr_b16 v[60:61], v212
	ds_read_b64_tr_b16 v[62:63], v212 offset:32
	ds_read_b64_tr_b16 v[64:65], v212 offset:64
	ds_read_b64_tr_b16 v[66:67], v212 offset:96
	s_nop 1
	v_mfma_f32_16x16x32_bf16 v[84:87], v[52:55], v[0:3], 0
	v_mfma_f32_16x16x32_bf16 v[84:87], v[56:59], v[4:7], v[84:87]
	s_nop 7
	v_add_u32_e32 v52, 0xa0, v77
	v_cmp_gt_u32_e32 vcc, s16, v52
	v_cmp_lt_i32_e64 s[44:45], -1, v79
	v_add_u32_e32 v53, 32, v77
	s_and_b64 vcc, s[44:45], vcc
	v_cndmask_b32_e32 v52, v245, v84, vcc
	v_cmp_lt_u32_e32 vcc, s17, v53
	v_cmp_lt_i32_e64 s[44:45], -2, v79
	s_and_b64 vcc, s[44:45], vcc
	v_add_u32_e32 v54, 0xa2, v77
	v_cndmask_b32_e32 v53, v245, v85, vcc
	v_cmp_gt_u32_e32 vcc, s16, v54
	v_cmp_lt_i32_e64 s[44:45], -3, v79
	s_and_b64 vcc, s[44:45], vcc
	v_add_u32_e32 v55, 0xa3, v77
	v_cndmask_b32_e32 v54, v245, v86, vcc
	v_cmp_gt_u32_e32 vcc, s16, v55
	v_cmp_lt_i32_e64 s[44:45], -4, v79
	s_and_b64 vcc, s[44:45], vcc
	v_cndmask_b32_e32 v55, v245, v87, vcc
	v_max_f32_e32 v56, v55, v55
	v_max_f32_e32 v57, v54, v54
	v_max_f32_e32 v56, v57, v56
	v_max3_f32 v56, v52, v53, v56
	v_mov_b32_e32 v57, v56
	s_nop 1
	v_permlane16_swap_b32_e32 v56, v57
	s_waitcnt lgkmcnt(0)
	v_max_f32_e32 v57, v57, v57
	v_max_f32_e32 v56, v56, v57
	v_mov_b32_e32 v57, v56
	s_nop 1
	v_permlane32_swap_b32_e32 v56, v57
	v_max_f32_e32 v57, v57, v57
	v_max_f32_e32 v56, v56, v56
	v_max_f32_e32 v56, v56, v57
	v_mul_f32_e32 v56, 0x3e38aa3b, v56
	v_cmp_gt_f32_e32 vcc, v56, v80
	s_cbranch_vccz .LBB0_458
	s_nop 0
	v_cndmask_b32_e32 v57, v76, v56, vcc
	v_sub_f32_e32 v56, v76, v57
	v_exp_f32_e32 v56, v56
	v_xor_b32_e32 v81, 0x80000000, v57
	v_mov_b32_e32 v76, v57
	v_mul_f32_e32 v82, v82, v56
	v_pk_mul_f32 v[50:51], v[50:51], v[56:57] op_sel_hi:[1,0]
	v_pk_mul_f32 v[48:49], v[48:49], v[56:57] op_sel_hi:[1,0]
	v_pk_mul_f32 v[70:71], v[70:71], v[56:57] op_sel_hi:[1,0]
	v_pk_mul_f32 v[68:69], v[68:69], v[56:57] op_sel_hi:[1,0]
	v_pk_mul_f32 v[14:15], v[14:15], v[56:57] op_sel_hi:[1,0]
	v_pk_mul_f32 v[12:13], v[12:13], v[56:57] op_sel_hi:[1,0]
	v_pk_mul_f32 v[10:11], v[10:11], v[56:57] op_sel_hi:[1,0]
	v_pk_mul_f32 v[8:9], v[8:9], v[56:57] op_sel_hi:[1,0]
	s_branch .LBB0_458
